# partial drain (vmcnt(6)) of the previous tile's stores before the FFN-up / projection main loops
# speedup vs baseline: 1.0184x; 1.0071x over previous
.LBB0_233:
	s_ashr_i32 s15, s14, 31
	s_lshl_b64 s[16:17], s[14:15], 19
	s_add_u32 s16, s26, s16
	s_addc_u32 s17, s27, s17
	s_and_b64 s[18:19], s[4:5], exec
	s_cselect_b32 s15, s17, s21
	s_cselect_b32 s42, s16, s20
	s_ashr_i32 s13, s12, 31
	s_lshl_b64 s[18:19], s[12:13], 19
	s_add_u32 s18, s28, s18
	s_addc_u32 s19, s29, s19
	s_and_b64 s[24:25], s[4:5], exec
	s_cselect_b32 s13, s19, s23
	s_cselect_b32 s43, s18, s22
	s_add_u32 s20, s20, 0x40080
	s_addc_u32 s21, s21, 0
	s_add_u32 s44, s22, 0x100
	v_mov_b32_e32 v2, 0
	s_addc_u32 s45, s23, 0
	s_mov_b32 s46, -2
	v_mov_b32_e32 v3, v2
	v_mov_b32_e32 v4, v2
	v_mov_b32_e32 v5, v2
	v_mov_b32_e32 v6, v2
	v_mov_b32_e32 v7, v2
	v_mov_b32_e32 v8, v2
	v_mov_b32_e32 v9, v2
	v_mov_b32_e32 v18, v2
	v_mov_b32_e32 v19, v2
	v_mov_b32_e32 v20, v2
	v_mov_b32_e32 v21, v2
	v_mov_b32_e32 v22, v2
	v_mov_b32_e32 v23, v2
	v_mov_b32_e32 v24, v2
	v_mov_b32_e32 v25, v2
	v_mov_b32_e32 v34, v2
	v_mov_b32_e32 v35, v2
	v_mov_b32_e32 v36, v2
	v_mov_b32_e32 v37, v2
	v_mov_b32_e32 v38, v2
	v_mov_b32_e32 v39, v2
	v_mov_b32_e32 v40, v2
	v_mov_b32_e32 v41, v2
	v_mov_b32_e32 v50, v2
	v_mov_b32_e32 v51, v2
	v_mov_b32_e32 v52, v2
	v_mov_b32_e32 v53, v2
	v_mov_b32_e32 v54, v2
	v_mov_b32_e32 v55, v2
	v_mov_b32_e32 v56, v2
	v_mov_b32_e32 v57, v2
	v_mov_b32_e32 v10, v2
	v_mov_b32_e32 v11, v2
	v_mov_b32_e32 v12, v2
	v_mov_b32_e32 v13, v2
	v_mov_b32_e32 v14, v2
	v_mov_b32_e32 v15, v2
	v_mov_b32_e32 v16, v2
	v_mov_b32_e32 v17, v2
	v_mov_b32_e32 v26, v2
	v_mov_b32_e32 v27, v2
	v_mov_b32_e32 v28, v2
	v_mov_b32_e32 v29, v2
	v_mov_b32_e32 v30, v2
	v_mov_b32_e32 v31, v2
	v_mov_b32_e32 v32, v2
	v_mov_b32_e32 v33, v2
	v_mov_b32_e32 v42, v2
	v_mov_b32_e32 v43, v2
	v_mov_b32_e32 v44, v2
	v_mov_b32_e32 v45, v2
	v_mov_b32_e32 v46, v2
	v_mov_b32_e32 v47, v2
	v_mov_b32_e32 v48, v2
	v_mov_b32_e32 v49, v2
	v_mov_b32_e32 v58, v2
	v_mov_b32_e32 v59, v2
	v_mov_b32_e32 v60, v2
	v_mov_b32_e32 v61, v2
	v_mov_b32_e32 v62, v2
	v_mov_b32_e32 v63, v2
	v_mov_b32_e32 v64, v2
	v_mov_b32_e32 v65, v2
	v_mov_b32_e32 v66, v2
	v_mov_b32_e32 v67, v2
	v_mov_b32_e32 v68, v2
	v_mov_b32_e32 v69, v2
	v_mov_b32_e32 v70, v2
	v_mov_b32_e32 v71, v2
	v_mov_b32_e32 v72, v2
	v_mov_b32_e32 v73, v2
	v_mov_b32_e32 v82, v2
	v_mov_b32_e32 v83, v2
	v_mov_b32_e32 v84, v2
	v_mov_b32_e32 v85, v2
	v_mov_b32_e32 v86, v2
	v_mov_b32_e32 v87, v2
	v_mov_b32_e32 v88, v2
	v_mov_b32_e32 v89, v2
	v_mov_b32_e32 v98, v2
	v_mov_b32_e32 v99, v2
	v_mov_b32_e32 v100, v2
	v_mov_b32_e32 v101, v2
	v_mov_b32_e32 v102, v2
	v_mov_b32_e32 v103, v2
	v_mov_b32_e32 v104, v2
	v_mov_b32_e32 v105, v2
	v_mov_b32_e32 v114, v2
	v_mov_b32_e32 v115, v2
	v_mov_b32_e32 v116, v2
	v_mov_b32_e32 v117, v2
	v_mov_b32_e32 v118, v2
	v_mov_b32_e32 v119, v2
	v_mov_b32_e32 v120, v2
	v_mov_b32_e32 v121, v2
	v_mov_b32_e32 v74, v2
	v_mov_b32_e32 v75, v2
	v_mov_b32_e32 v76, v2
	v_mov_b32_e32 v77, v2
	v_mov_b32_e32 v78, v2
	v_mov_b32_e32 v79, v2
	v_mov_b32_e32 v80, v2
	v_mov_b32_e32 v81, v2
	v_mov_b32_e32 v90, v2
	v_mov_b32_e32 v91, v2
	v_mov_b32_e32 v92, v2
	v_mov_b32_e32 v93, v2
	v_mov_b32_e32 v94, v2
	v_mov_b32_e32 v95, v2
	v_mov_b32_e32 v96, v2
	v_mov_b32_e32 v97, v2
	v_mov_b32_e32 v106, v2
	v_mov_b32_e32 v107, v2
	v_mov_b32_e32 v108, v2
	v_mov_b32_e32 v109, v2
	v_mov_b32_e32 v110, v2
	v_mov_b32_e32 v111, v2
	v_mov_b32_e32 v112, v2
	v_mov_b32_e32 v113, v2
	v_mov_b32_e32 v122, v2
	v_mov_b32_e32 v123, v2
	v_mov_b32_e32 v124, v2
	v_mov_b32_e32 v125, v2
	v_mov_b32_e32 v126, v2
	v_mov_b32_e32 v127, v2
	v_mov_b32_e32 v128, v2
	v_mov_b32_e32 v129, v2
	s_waitcnt vmcnt(6)

.LBB0_393:
	s_ashr_i32 s17, s16, 31
	s_lshl_b64 s[18:19], s[16:17], 19
	s_add_u32 s18, s26, s18
	s_addc_u32 s19, s27, s19
	s_and_b64 s[20:21], s[8:9], exec
	s_cselect_b32 s17, s19, s11
	s_cselect_b32 s42, s18, s10
	s_ashr_i32 s15, s14, 31
	s_lshl_b64 s[20:21], s[14:15], 19
	s_add_u32 s20, s28, s20
	s_addc_u32 s21, s29, s21
	s_and_b64 s[24:25], s[8:9], exec
	s_cselect_b32 s15, s21, s23
	s_cselect_b32 s43, s20, s22
	s_add_u32 s10, s10, 0x40080
	s_addc_u32 s11, s11, 0
	s_add_u32 s44, s22, 0x100
	v_mov_b32_e32 v2, 0
	s_addc_u32 s45, s23, 0
	s_mov_b32 s46, -2
	v_mov_b32_e32 v3, v2
	v_mov_b32_e32 v4, v2
	v_mov_b32_e32 v5, v2
	v_mov_b32_e32 v6, v2
	v_mov_b32_e32 v7, v2
	v_mov_b32_e32 v8, v2
	v_mov_b32_e32 v9, v2
	v_mov_b32_e32 v18, v2
	v_mov_b32_e32 v19, v2
	v_mov_b32_e32 v20, v2
	v_mov_b32_e32 v21, v2
	v_mov_b32_e32 v22, v2
	v_mov_b32_e32 v23, v2
	v_mov_b32_e32 v24, v2
	v_mov_b32_e32 v25, v2
	v_mov_b32_e32 v34, v2
	v_mov_b32_e32 v35, v2
	v_mov_b32_e32 v36, v2
	v_mov_b32_e32 v37, v2
	v_mov_b32_e32 v38, v2
	v_mov_b32_e32 v39, v2
	v_mov_b32_e32 v40, v2
	v_mov_b32_e32 v41, v2
	v_mov_b32_e32 v50, v2
	v_mov_b32_e32 v51, v2
	v_mov_b32_e32 v52, v2
	v_mov_b32_e32 v53, v2
	v_mov_b32_e32 v54, v2
	v_mov_b32_e32 v55, v2
	v_mov_b32_e32 v56, v2
	v_mov_b32_e32 v57, v2
	v_mov_b32_e32 v10, v2
	v_mov_b32_e32 v11, v2
	v_mov_b32_e32 v12, v2
	v_mov_b32_e32 v13, v2
	v_mov_b32_e32 v14, v2
	v_mov_b32_e32 v15, v2
	v_mov_b32_e32 v16, v2
	v_mov_b32_e32 v17, v2
	v_mov_b32_e32 v26, v2
	v_mov_b32_e32 v27, v2
	v_mov_b32_e32 v28, v2
	v_mov_b32_e32 v29, v2
	v_mov_b32_e32 v30, v2
	v_mov_b32_e32 v31, v2
	v_mov_b32_e32 v32, v2
	v_mov_b32_e32 v33, v2
	v_mov_b32_e32 v42, v2
	v_mov_b32_e32 v43, v2
	v_mov_b32_e32 v44, v2
	v_mov_b32_e32 v45, v2
	v_mov_b32_e32 v46, v2
	v_mov_b32_e32 v47, v2
	v_mov_b32_e32 v48, v2
	v_mov_b32_e32 v49, v2
	v_mov_b32_e32 v58, v2
	v_mov_b32_e32 v59, v2
	v_mov_b32_e32 v60, v2
	v_mov_b32_e32 v61, v2
	v_mov_b32_e32 v62, v2
	v_mov_b32_e32 v63, v2
	v_mov_b32_e32 v64, v2
	v_mov_b32_e32 v65, v2
	v_mov_b32_e32 v66, v2
	v_mov_b32_e32 v67, v2
	v_mov_b32_e32 v68, v2
	v_mov_b32_e32 v69, v2
	v_mov_b32_e32 v70, v2
	v_mov_b32_e32 v71, v2
	v_mov_b32_e32 v72, v2
	v_mov_b32_e32 v73, v2
	v_mov_b32_e32 v82, v2
	v_mov_b32_e32 v83, v2
	v_mov_b32_e32 v84, v2
	v_mov_b32_e32 v85, v2
	v_mov_b32_e32 v86, v2
	v_mov_b32_e32 v87, v2
	v_mov_b32_e32 v88, v2
	v_mov_b32_e32 v89, v2
	v_mov_b32_e32 v98, v2
	v_mov_b32_e32 v99, v2
	v_mov_b32_e32 v100, v2
	v_mov_b32_e32 v101, v2
	v_mov_b32_e32 v102, v2
	v_mov_b32_e32 v103, v2
	v_mov_b32_e32 v104, v2
	v_mov_b32_e32 v105, v2
	v_mov_b32_e32 v114, v2
	v_mov_b32_e32 v115, v2
	v_mov_b32_e32 v116, v2
	v_mov_b32_e32 v117, v2
	v_mov_b32_e32 v118, v2
	v_mov_b32_e32 v119, v2
	v_mov_b32_e32 v120, v2
	v_mov_b32_e32 v121, v2
	v_mov_b32_e32 v74, v2
	v_mov_b32_e32 v75, v2
	v_mov_b32_e32 v76, v2
	v_mov_b32_e32 v77, v2
	v_mov_b32_e32 v78, v2
	v_mov_b32_e32 v79, v2
	v_mov_b32_e32 v80, v2
	v_mov_b32_e32 v81, v2
	v_mov_b32_e32 v90, v2
	v_mov_b32_e32 v91, v2
	v_mov_b32_e32 v92, v2
	v_mov_b32_e32 v93, v2
	v_mov_b32_e32 v94, v2
	v_mov_b32_e32 v95, v2
	v_mov_b32_e32 v96, v2
	v_mov_b32_e32 v97, v2
	v_mov_b32_e32 v106, v2
	v_mov_b32_e32 v107, v2
	v_mov_b32_e32 v108, v2
	v_mov_b32_e32 v109, v2
	v_mov_b32_e32 v110, v2
	v_mov_b32_e32 v111, v2
	v_mov_b32_e32 v112, v2
	v_mov_b32_e32 v113, v2
	v_mov_b32_e32 v122, v2
	v_mov_b32_e32 v123, v2
	v_mov_b32_e32 v124, v2
	v_mov_b32_e32 v125, v2
	v_mov_b32_e32 v126, v2
	v_mov_b32_e32 v127, v2
	v_mov_b32_e32 v128, v2
	v_mov_b32_e32 v129, v2
	s_waitcnt vmcnt(6)

.LBB0_1601:
	s_ashr_i32 s15, s14, 31
	s_lshl_b64 s[16:17], s[14:15], 19
	s_add_u32 s16, s26, s16
	s_addc_u32 s17, s27, s17
	s_and_b64 s[18:19], s[6:7], exec
	s_cselect_b32 s15, s17, s21
	s_cselect_b32 s42, s16, s20
	s_ashr_i32 s13, s12, 31
	s_lshl_b64 s[18:19], s[12:13], 19
	s_add_u32 s18, s28, s18
	s_addc_u32 s19, s29, s19
	s_and_b64 s[24:25], s[6:7], exec
	s_cselect_b32 s13, s19, s23
	s_cselect_b32 s43, s18, s22
	s_add_u32 s20, s20, 0x40080
	s_addc_u32 s21, s21, 0
	s_add_u32 s44, s22, 0x100
	v_mov_b32_e32 v2, 0
	s_addc_u32 s45, s23, 0
	s_mov_b32 s46, -2
	v_mov_b32_e32 v3, v2
	v_mov_b32_e32 v4, v2
	v_mov_b32_e32 v5, v2
	v_mov_b32_e32 v6, v2
	v_mov_b32_e32 v7, v2
	v_mov_b32_e32 v8, v2
	v_mov_b32_e32 v9, v2
	v_mov_b32_e32 v18, v2
	v_mov_b32_e32 v19, v2
	v_mov_b32_e32 v20, v2
	v_mov_b32_e32 v21, v2
	v_mov_b32_e32 v22, v2
	v_mov_b32_e32 v23, v2
	v_mov_b32_e32 v24, v2
	v_mov_b32_e32 v25, v2
	v_mov_b32_e32 v34, v2
	v_mov_b32_e32 v35, v2
	v_mov_b32_e32 v36, v2
	v_mov_b32_e32 v37, v2
	v_mov_b32_e32 v38, v2
	v_mov_b32_e32 v39, v2
	v_mov_b32_e32 v40, v2
	v_mov_b32_e32 v41, v2
	v_mov_b32_e32 v50, v2
	v_mov_b32_e32 v51, v2
	v_mov_b32_e32 v52, v2
	v_mov_b32_e32 v53, v2
	v_mov_b32_e32 v54, v2
	v_mov_b32_e32 v55, v2
	v_mov_b32_e32 v56, v2
	v_mov_b32_e32 v57, v2
	v_mov_b32_e32 v10, v2
	v_mov_b32_e32 v11, v2
	v_mov_b32_e32 v12, v2
	v_mov_b32_e32 v13, v2
	v_mov_b32_e32 v14, v2
	v_mov_b32_e32 v15, v2
	v_mov_b32_e32 v16, v2
	v_mov_b32_e32 v17, v2
	v_mov_b32_e32 v26, v2
	v_mov_b32_e32 v27, v2
	v_mov_b32_e32 v28, v2
	v_mov_b32_e32 v29, v2
	v_mov_b32_e32 v30, v2
	v_mov_b32_e32 v31, v2
	v_mov_b32_e32 v32, v2
	v_mov_b32_e32 v33, v2
	v_mov_b32_e32 v42, v2
	v_mov_b32_e32 v43, v2
	v_mov_b32_e32 v44, v2
	v_mov_b32_e32 v45, v2
	v_mov_b32_e32 v46, v2
	v_mov_b32_e32 v47, v2
	v_mov_b32_e32 v48, v2
	v_mov_b32_e32 v49, v2
	v_mov_b32_e32 v58, v2
	v_mov_b32_e32 v59, v2
	v_mov_b32_e32 v60, v2
	v_mov_b32_e32 v61, v2
	v_mov_b32_e32 v62, v2
	v_mov_b32_e32 v63, v2
	v_mov_b32_e32 v64, v2
	v_mov_b32_e32 v65, v2
	v_mov_b32_e32 v66, v2
	v_mov_b32_e32 v67, v2
	v_mov_b32_e32 v68, v2
	v_mov_b32_e32 v69, v2
	v_mov_b32_e32 v70, v2
	v_mov_b32_e32 v71, v2
	v_mov_b32_e32 v72, v2
	v_mov_b32_e32 v73, v2
	v_mov_b32_e32 v82, v2
	v_mov_b32_e32 v83, v2
	v_mov_b32_e32 v84, v2
	v_mov_b32_e32 v85, v2
	v_mov_b32_e32 v86, v2
	v_mov_b32_e32 v87, v2
	v_mov_b32_e32 v88, v2
	v_mov_b32_e32 v89, v2
	v_mov_b32_e32 v98, v2
	v_mov_b32_e32 v99, v2
	v_mov_b32_e32 v100, v2
	v_mov_b32_e32 v101, v2
	v_mov_b32_e32 v102, v2
	v_mov_b32_e32 v103, v2
	v_mov_b32_e32 v104, v2
	v_mov_b32_e32 v105, v2
	v_mov_b32_e32 v114, v2
	v_mov_b32_e32 v115, v2
	v_mov_b32_e32 v116, v2
	v_mov_b32_e32 v117, v2
	v_mov_b32_e32 v118, v2
	v_mov_b32_e32 v119, v2
	v_mov_b32_e32 v120, v2
	v_mov_b32_e32 v121, v2
	v_mov_b32_e32 v74, v2
	v_mov_b32_e32 v75, v2
	v_mov_b32_e32 v76, v2
	v_mov_b32_e32 v77, v2
	v_mov_b32_e32 v78, v2
	v_mov_b32_e32 v79, v2
	v_mov_b32_e32 v80, v2
	v_mov_b32_e32 v81, v2
	v_mov_b32_e32 v90, v2
	v_mov_b32_e32 v91, v2
	v_mov_b32_e32 v92, v2
	v_mov_b32_e32 v93, v2
	v_mov_b32_e32 v94, v2
	v_mov_b32_e32 v95, v2
	v_mov_b32_e32 v96, v2
	v_mov_b32_e32 v97, v2
	v_mov_b32_e32 v106, v2
	v_mov_b32_e32 v107, v2
	v_mov_b32_e32 v108, v2
	v_mov_b32_e32 v109, v2
	v_mov_b32_e32 v110, v2
	v_mov_b32_e32 v111, v2
	v_mov_b32_e32 v112, v2
	v_mov_b32_e32 v113, v2
	v_mov_b32_e32 v122, v2
	v_mov_b32_e32 v123, v2
	v_mov_b32_e32 v124, v2
	v_mov_b32_e32 v125, v2
	v_mov_b32_e32 v126, v2
	v_mov_b32_e32 v127, v2
	v_mov_b32_e32 v128, v2
	v_mov_b32_e32 v129, v2
	s_waitcnt vmcnt(6)
